# P4 first-iteration x rows prefetched in the shadow of grid barrier 4 (waves 1-7), dummy loads keep the vmcnt order
# baseline (speedup 1.0000x reference)
; __device__ __forceinline__ unsigned xb_ld(unsigned* p)              { return __hip_atomic_load(p, __ATOMIC_RELAXED, __HIP_MEMORY_SCOPE_AGENT); }
; __device__ __forceinline__ unsigned xb_add(unsigned* p, unsigned v) { return __hip_atomic_fetch_add(p, v, __ATOMIC_RELAXED, __HIP_MEMORY_SCOPE_AGENT); }
; __device__ __forceinline__ void xcd_barrier(const XcdBarrier& b) {
;     asm volatile("s_waitcnt vmcnt(0)" ::: "memory");
;     __syncthreads();
;     if (threadIdx.x == 0) {
;         unsigned* bar = b.bar;
;         __builtin_amdgcn_s_waitcnt(0);
;         unsigned nloc = b.st[0], nx = b.st[1];
;         if (nloc == 0u) { xcd_barrier_complete(bar, b.x, nloc, nx); b.st[0] = nloc; b.st[1] = nx; }
;         const unsigned old = xb_add(&bar[XB_XSUB(b.x)], 1u);
;         const unsigned gen = old / nloc;
;         if (old + 1u == (gen + 1u) * nloc) {
;             __builtin_amdgcn_fence(__ATOMIC_RELEASE, "agent");
;             asm volatile("s_waitcnt vmcnt(0)" ::: "memory");
;             const unsigned og = xb_add(&bar[XB_TOP], 1u);
;             const unsigned tg = og / nx;
;             if (og + 1u == (tg + 1u) * nx) xb_add(&bar[XB_TOPGEN], 1u);
;             else XB_SPIN(xb_ld(&bar[XB_TOPGEN]) == tg, bar);
;             __builtin_amdgcn_fence(__ATOMIC_ACQUIRE, "agent");
;             xb_add(&bar[XB_XGEN(b.x)], 1u);
;             asm volatile("s_waitcnt vmcnt(0)" ::: "memory");
;         } else {
;             XB_SPIN(xb_ld(&bar[XB_XGEN(b.x)]) == gen, bar);
;             __builtin_amdgcn_fence(__ATOMIC_ACQUIRE, "agent");
;             asm volatile("s_waitcnt vmcnt(0)" ::: "memory");
;         }
; __global__ void __launch_bounds__(NTHR, 2) mk_fwd(Args a) {
;     ...
;             for (int r = 0; r < 2; ++r) { const int m = m0 + r * NGW; const bool ok = m < NTOK; const int mm = ok ? m : m0;
;                 part[r] = (lane < 32) ? OSS[(size_t)mm * 32 + lane] : 0.f;
;                 const f32x4* xr = (const f32x4*)(x + (size_t)mm * DMODEL) + lane; const u32x2* ob = (const u32x2*)(OutB + (size_t)mm * DMODEL) + lane;
; #pragma unroll
;                 for (int j = 0; j < 8; ++j) { xv[r][j] = __builtin_nontemporal_load(xr + 64 * j); ov[r][j] = __builtin_nontemporal_load(ob + 64 * j); } }
.LBB0_787:
	s_waitcnt vmcnt(0) lgkmcnt(0)
	s_barrier
	s_cmp_eq_u32 s33, 0
	s_cbranch_scc1 .Lgb4_proto
	s_lshl_b32 s4, s2, 3
	s_add_i32 s4, s4, s33
	s_lshl_b32 s4, s4, 13
	s_add_u32 s6, s52, s4
	s_addc_u32 s7, s53, 0
	v_lshlrev_b32_e32 v152, 4, v255
	v_mov_b32_e32 v153, 0
	s_nop 1
	global_load_dwordx4 v[92:95], v152, s[6:7] nt
	global_load_dwordx4 v[88:91], v152, s[6:7] offset:1024 nt
	global_load_dwordx4 v[84:87], v152, s[6:7] offset:2048 nt
	global_load_dwordx4 v[80:83], v152, s[6:7] offset:3072 nt
	s_add_u32 s6, s6, 0x1000
	s_addc_u32 s7, s7, 0
	global_load_dwordx4 v[76:79], v152, s[6:7] nt
	global_load_dwordx4 v[72:75], v152, s[6:7] offset:1024 nt
	global_load_dwordx4 v[68:71], v152, s[6:7] offset:2048 nt
	global_load_dwordx4 v[60:63], v152, s[6:7] offset:3072 nt
	s_add_u32 s6, s6, 0xfff000
	s_addc_u32 s7, s7, 0
	global_load_dwordx4 v[64:67], v152, s[6:7] nt
	global_load_dwordx4 v[56:59], v152, s[6:7] offset:1024 nt
	global_load_dwordx4 v[52:55], v152, s[6:7] offset:2048 nt
	global_load_dwordx4 v[44:47], v152, s[6:7] offset:3072 nt
	s_add_u32 s6, s6, 0x1000
	s_addc_u32 s7, s7, 0
	global_load_dwordx4 v[48:51], v152, s[6:7] nt
	global_load_dwordx4 v[40:43], v152, s[6:7] offset:1024 nt
	s_branch .Lgb4_close
.Lgb4_proto:
	v_cmp_eq_u32_e32 vcc, 0, v0
	s_and_saveexec_b64 s[0:1], vcc
	s_cbranch_execz .Lgb4_join
	v_mov_b32_e32 v1, s85
	ds_read_b32 v2, v1
	ds_read_b32 v3, v1 offset:4
	s_lshl_b32 s4, s84, 8
	s_add_u32 s4, s22, s4
	s_addc_u32 s5, s23, 0
	v_mov_b32_e32 v4, 0x1000
	v_mov_b32_e32 v5, 1
	global_atomic_add v5, v4, v5, s[4:5] offset:1024 sc0
	s_waitcnt lgkmcnt(0)
	v_readfirstlane_b32 s6, v2
	v_readfirstlane_b32 s7, v3
	s_nop 3
	s_mul_i32 s14, s6, 5
	s_add_i32 s14, s14, -1
	s_mul_i32 s7, s7, 5
	s_waitcnt vmcnt(0)
	v_readfirstlane_b32 s15, v5
	v_mov_b32_e32 v4, 0x3400
	s_nop 3
	s_cmp_lg_u32 s15, s14
	s_cbranch_scc1 .Lgb4_poll
	buffer_wbl2 sc1
	s_waitcnt vmcnt(0)
	v_mov_b32_e32 v5, 1
	global_atomic_add v4, v5, s[22:23]

; __global__ void __launch_bounds__(NTHR, 2) mk_fwd(Args a) {
;     ...
;             for (int r = 0; r < 2; ++r) { const int m = m0 + r * NGW; const bool ok = m < NTOK; const int mm = ok ? m : m0;
;                 part[r] = (lane < 32) ? OSS[(size_t)mm * 32 + lane] : 0.f;
;                 const f32x4* xr = (const f32x4*)(x + (size_t)mm * DMODEL) + lane; const u32x2* ob = (const u32x2*)(OutB + (size_t)mm * DMODEL) + lane;
; #pragma unroll
;                 for (int j = 0; j < 8; ++j) { xv[r][j] = __builtin_nontemporal_load(xr + 64 * j); ov[r][j] = __builtin_nontemporal_load(ob + 64 * j); } }
.Lgb4_join:
	s_or_b64 exec, exec, s[0:1]
	s_lshl_b32 s4, s2, 3
	s_add_i32 s4, s4, s33
	s_lshl_b32 s4, s4, 13
	s_add_u32 s6, s52, s4
	s_addc_u32 s7, s53, 0
	v_lshlrev_b32_e32 v152, 4, v255
	v_mov_b32_e32 v153, 0
	s_nop 1
	global_load_dwordx4 v[92:95], v152, s[6:7] nt
	global_load_dwordx4 v[88:91], v152, s[6:7] offset:1024 nt
	global_load_dwordx4 v[84:87], v152, s[6:7] offset:2048 nt
	global_load_dwordx4 v[80:83], v152, s[6:7] offset:3072 nt
	s_add_u32 s6, s6, 0x1000
	s_addc_u32 s7, s7, 0
	global_load_dwordx4 v[76:79], v152, s[6:7] nt
	global_load_dwordx4 v[72:75], v152, s[6:7] offset:1024 nt
	global_load_dwordx4 v[68:71], v152, s[6:7] offset:2048 nt
	global_load_dwordx4 v[60:63], v152, s[6:7] offset:3072 nt
	s_add_u32 s6, s6, 0xfff000
	s_addc_u32 s7, s7, 0
	global_load_dwordx4 v[64:67], v152, s[6:7] nt
	global_load_dwordx4 v[56:59], v152, s[6:7] offset:1024 nt
	global_load_dwordx4 v[52:55], v152, s[6:7] offset:2048 nt
	global_load_dwordx4 v[44:47], v152, s[6:7] offset:3072 nt
	s_add_u32 s6, s6, 0x1000
	s_addc_u32 s7, s7, 0
	global_load_dwordx4 v[48:51], v152, s[6:7] nt
	global_load_dwordx4 v[40:43], v152, s[6:7] offset:1024 nt

; __global__ void __launch_bounds__(NTHR, 2) mk_fwd(Args a) {
;     ...
;         const int gw = bx * NWAVES + wave, NGW = G * NWAVES;
;         f32x4 gv[8];
; #pragma unroll
;         for (int j = 0; j < 8; ++j) gv[j] = ((const f32x4*)norm_post)[lane + 64 * j];
;         for (int m0 = gw; m0 < NTOK; m0 += 2 * NGW) {
.LBB0_836:
	s_cmp_gt_i32 s26, 5
	s_cselect_b64 s[0:1], -1, 0
	s_cmp_lt_i32 s27, 6
	s_cselect_b64 s[4:5], -1, 0
	s_or_b64 s[0:1], s[0:1], s[4:5]
	s_and_b64 vcc, exec, s[0:1]
	s_cbranch_vccnz .LBB0_846
	s_lshl_b32 s0, s2, 3
	s_add_i32 s4, s33, s0
	s_cmpk_gt_i32 s4, 0x3fff
	s_cbranch_scc1 .LBB0_846
	v_lshlrev_b32_e32 v32, 4, v255
	v_mov_b32_e32 v33, 0
	v_lshl_add_u64 v[0:1], s[48:49], 0, v[32:33]
	v_add_co_u32_e32 v34, vcc, 0x1000, v0
	s_lshl_b32 s14, s3, 3
	s_nop 0
	v_addc_co_u32_e32 v35, vcc, 0, v1, vcc
	global_load_dwordx4 v[0:3], v[34:35], off offset:3072
	s_waitcnt lgkmcnt(0)
	global_load_dwordx4 v[4:7], v[34:35], off offset:2048
	global_load_dwordx4 v[8:11], v[34:35], off offset:1024
	global_load_dwordx4 v[12:15], v[34:35], off
	global_load_dwordx4 v[16:19], v32, s[48:49] offset:3072
	global_load_dwordx4 v[20:23], v32, s[48:49] offset:2048
	global_load_dwordx4 v[24:27], v32, s[48:49] offset:1024
	global_load_dwordx4 v[28:31], v32, s[48:49]
	v_lshlrev_b32_e32 v34, 3, v255
	v_mov_b32_e32 v35, v33
	v_lshl_add_u64 v[98:99], s[30:31], 0, v[34:35]
	v_lshlrev_b32_e32 v34, 2, v255
	v_lshl_add_u64 v[100:101], s[12:13], 0, v[34:35]
	v_mbcnt_lo_u32_b32 v34, -1, 0
	v_mbcnt_hi_u32_b32 v34, -1, v34
	v_and_b32_e32 v35, 64, v34
	v_add_u32_e32 v35, 64, v35
	v_xor_b32_e32 v36, 1, v34
	v_cmp_lt_i32_e32 vcc, v36, v35
	s_movk_i32 s15, 0x1000
	v_cmp_gt_u32_e64 s[0:1], 32, v255
	v_cndmask_b32_e32 v36, v34, v36, vcc
	v_lshlrev_b32_e32 v136, 2, v36
	v_xor_b32_e32 v36, 2, v34
	v_cmp_lt_i32_e32 vcc, v36, v35
	v_lshl_add_u64 v[96:97], s[52:53], 0, v[32:33]
	v_lshl_add_u64 v[102:103], s[50:51], 0, v[32:33]
	v_cndmask_b32_e32 v36, v34, v36, vcc
	v_lshlrev_b32_e32 v137, 2, v36
	v_xor_b32_e32 v36, 4, v34
	v_cmp_lt_i32_e32 vcc, v36, v35
	s_lshl_b32 s16, s3, 4
	v_mov_b32_e32 v142, 0x358637bd
	v_cndmask_b32_e32 v36, v34, v36, vcc
	v_lshlrev_b32_e32 v138, 2, v36
	v_xor_b32_e32 v36, 8, v34
	v_cmp_lt_i32_e32 vcc, v36, v35
	s_mov_b32 s17, 0xf800000
	v_mov_b32_e32 v143, 0x260
	v_cndmask_b32_e32 v36, v34, v36, vcc
	v_lshlrev_b32_e32 v139, 2, v36
	v_xor_b32_e32 v36, 16, v34
	v_cmp_lt_i32_e32 vcc, v36, v35
	s_nop 1
	v_cndmask_b32_e32 v36, v34, v36, vcc
	v_lshlrev_b32_e32 v140, 2, v36
	v_xor_b32_e32 v36, 32, v34
	v_cmp_lt_i32_e32 vcc, v36, v35
	s_nop 1
	v_cndmask_b32_e32 v34, v34, v36, vcc
	v_lshlrev_b32_e32 v141, 2, v34
	s_branch .LBB0_840

; __device__ __forceinline__ float bf_lo(unsigned u) { return __uint_as_float(u << 16); }
; __device__ __forceinline__ float bf_hi(unsigned u) { return __uint_as_float(u & 0xffff0000u); }
; __global__ void __launch_bounds__(NTHR, 2) mk_fwd(Args a) {
;     ...
;             for (int r = 0; r < 2; ++r) { const int m = m0 + r * NGW; const bool ok = m < NTOK; const int mm = ok ? m : m0;
;                 part[r] = (lane < 32) ? OSS[(size_t)mm * 32 + lane] : 0.f;
;                 const f32x4* xr = (const f32x4*)(x + (size_t)mm * DMODEL) + lane; const u32x2* ob = (const u32x2*)(OutB + (size_t)mm * DMODEL) + lane;
; #pragma unroll
;                 for (int j = 0; j < 8; ++j) { xv[r][j] = __builtin_nontemporal_load(xr + 64 * j); ov[r][j] = __builtin_nontemporal_load(ob + 64 * j); } }
; #pragma unroll
;             for (int r = 0; r < 2; ++r) { const int m = m0 + r * NGW;
;                 const float rs = 1.0f / sqrtf(wave_sum(part[r]) * (1.0f / DMODEL) + EPS);
;                 if (m < NTOK) { f32x4* orow = (f32x4*)(a.out + (size_t)m * DMODEL) + lane;
; #pragma unroll
;                     for (int j = 0; j < 8; ++j) { const f32x4 xx = xv[r][j], g4 = gv[j]; const u32x2 o = ov[r][j];
;                         f32x4 res; res[0] = xx[0] + bf_lo(o.x) * rs * g4[0]; res[1] = xx[1] + bf_hi(o.x) * rs * g4[1]; res[2] = xx[2] + bf_lo(o.y) * rs * g4[2]; res[3] = xx[3] + bf_hi(o.y) * rs * g4[3];
;                         __builtin_nontemporal_store(res, orow + 64 * j); } } }
.LBB0_842:
	s_or_b64 exec, exec, s[2:3]
	s_lshl_b64 s[10:11], s[4:5], 13
	v_lshl_add_u64 v[34:35], v[96:97], 0, s[10:11]
	s_lshl_b64 s[2:3], s[4:5], 12
	v_lshl_add_u64 v[36:37], v[98:99], 0, s[2:3]
	s_cmpk_lt_i32 s4, 0x800
	s_cbranch_scc1 .Lp4_dmyA0
	global_load_dwordx4 v[92:95], v[34:35], off nt
	global_load_dwordx4 v[88:91], v[34:35], off offset:1024 nt
	global_load_dwordx4 v[84:87], v[34:35], off offset:2048 nt
	global_load_dwordx4 v[80:83], v[34:35], off offset:3072 nt
.Lp4_retA0:
	global_load_dwordx2 v[134:135], v[36:37], off nt
	global_load_dwordx2 v[132:133], v[36:37], off offset:512 nt
	global_load_dwordx2 v[130:131], v[36:37], off offset:1024 nt
	global_load_dwordx2 v[128:129], v[36:37], off offset:1536 nt
	v_add_co_u32_e32 v34, vcc, 0x1000, v34
	s_add_i32 s6, s14, s4
	s_nop 0
	v_addc_co_u32_e32 v35, vcc, 0, v35, vcc
	s_waitcnt lgkmcnt(0)
	s_cmpk_lt_i32 s4, 0x800
	s_cbranch_scc1 .Lp4_dmyA4
	global_load_dwordx4 v[76:79], v[34:35], off nt
	global_load_dwordx4 v[72:75], v[34:35], off offset:1024 nt
	global_load_dwordx4 v[68:71], v[34:35], off offset:2048 nt
	global_load_dwordx4 v[60:63], v[34:35], off offset:3072 nt
.Lp4_retA4:
	global_load_dwordx2 v[126:127], v[36:37], off offset:2048 nt
	global_load_dwordx2 v[124:125], v[36:37], off offset:2560 nt
	global_load_dwordx2 v[122:123], v[36:37], off offset:3072 nt
	global_load_dwordx2 v[118:119], v[36:37], off offset:3584 nt
	s_cmpk_lt_i32 s6, 0x4000
	s_cselect_b64 s[8:9], -1, 0
	s_and_b64 s[2:3], s[8:9], exec
	s_cselect_b32 s2, s6, s4
	s_ashr_i32 s3, s2, 31
	v_mov_b32_e32 v144, 0
	s_and_saveexec_b64 s[12:13], s[0:1]
	s_cbranch_execz .LBB0_844
	s_lshl_b64 s[18:19], s[2:3], 7
	v_lshl_add_u64 v[34:35], v[100:101], 0, s[18:19]
	global_load_dword v144, v[34:35], off
.LBB0_844:
	s_or_b64 exec, exec, s[12:13]
	s_waitcnt vmcnt(16)
	ds_bpermute_b32 v33, v136, v32
	s_lshl_b64 s[12:13], s[2:3], 13
	s_lshl_b64 s[2:3], s[2:3], 12
	v_lshl_add_u64 v[104:105], v[98:99], 0, s[2:3]
	s_waitcnt vmcnt(11)
	v_and_b32_e32 v151, 0xffff0000, v134
	s_waitcnt lgkmcnt(0)
	v_add_f32_e32 v32, v32, v33
	ds_bpermute_b32 v33, v137, v32
	s_waitcnt lgkmcnt(0)
	v_add_f32_e32 v34, v32, v33
	ds_bpermute_b32 v35, v138, v34
	v_lshl_add_u64 v[32:33], v[96:97], 0, s[12:13]
	s_cmpk_lt_i32 s4, 0x800
	s_cbranch_scc1 .Lp4_dmyB0
	global_load_dwordx4 v[64:67], v[32:33], off nt
	global_load_dwordx4 v[56:59], v[32:33], off offset:1024 nt
	global_load_dwordx4 v[52:55], v[32:33], off offset:2048 nt
	global_load_dwordx4 v[44:47], v[32:33], off offset:3072 nt
.Lp4_retB0:
	v_add_co_u32_e32 v32, vcc, 0x1000, v32
	s_waitcnt lgkmcnt(0)
	v_add_f32_e32 v34, v34, v35
	ds_bpermute_b32 v35, v139, v34
	v_addc_co_u32_e32 v33, vcc, 0, v33, vcc
	global_load_dwordx2 v[120:121], v[104:105], off nt
	global_load_dwordx2 v[116:117], v[104:105], off offset:512 nt
	global_load_dwordx2 v[114:115], v[104:105], off offset:1024 nt
	global_load_dwordx2 v[110:111], v[104:105], off offset:1536 nt
	s_waitcnt lgkmcnt(0)
	v_add_f32_e32 v34, v34, v35
	ds_bpermute_b32 v35, v140, v34
	s_waitcnt lgkmcnt(0)
	v_add_f32_e32 v34, v34, v35
	ds_bpermute_b32 v35, v141, v34
	s_waitcnt lgkmcnt(0)
	v_add_f32_e32 v34, v34, v35
	v_fmamk_f32 v34, v34, 0x3a000000, v142
	v_mul_f32_e32 v35, 0x4f800000, v34
	v_cmp_gt_f32_e32 vcc, s17, v34
	s_nop 1
	v_cndmask_b32_e32 v106, v34, v35, vcc
	v_sqrt_f32_e32 v107, v106
	s_cmpk_lt_i32 s4, 0x800
	s_cbranch_scc1 .Lp4_dmyB4
	global_load_dwordx4 v[48:51], v[32:33], off nt
	global_load_dwordx4 v[40:43], v[32:33], off offset:1024 nt
.Lp4_retB4:
	global_load_dwordx4 v[36:39], v[32:33], off offset:2048 nt
	s_nop 0
	global_load_dwordx4 v[32:35], v[32:33], off offset:3072 nt
	v_add_u32_e32 v108, -1, v107
	v_add_u32_e32 v109, 1, v107
	v_fma_f32 v112, -v108, v107, v106
	v_fma_f32 v113, -v109, v107, v106
	v_cmp_ge_f32_e64 s[2:3], 0, v112
	s_nop 1
	v_cndmask_b32_e64 v107, v107, v108, s[2:3]
	v_cmp_lt_f32_e64 s[2:3], 0, v113
	s_nop 1
	v_cndmask_b32_e64 v107, v107, v109, s[2:3]
	v_mul_f32_e32 v108, 0x37800000, v107
	v_cndmask_b32_e32 v107, v107, v108, vcc
	v_cmp_class_f32_e32 vcc, v106, v143
	s_nop 1
	v_cndmask_b32_e32 v145, v107, v106, vcc
	global_load_dwordx2 v[112:113], v[104:105], off offset:2048 nt
	global_load_dwordx2 v[108:109], v[104:105], off offset:2560 nt
	global_load_dwordx2 v[106:107], v[104:105], off offset:3072 nt
	s_nop 0
	global_load_dwordx2 v[104:105], v[104:105], off offset:3584 nt
	v_div_scale_f32 v146, s[2:3], v145, v145, 1.0
	v_rcp_f32_e32 v147, v146
	s_nop 0
	v_fma_f32 v148, -v146, v147, 1.0
	v_fmac_f32_e32 v147, v148, v147
	v_div_scale_f32 v148, vcc, 1.0, v145, 1.0
	v_mul_f32_e32 v149, v148, v147
	v_fma_f32 v150, -v146, v149, v148
	v_fmac_f32_e32 v149, v150, v147
	v_fma_f32 v146, -v146, v149, v148
	v_div_fmas_f32 v146, v146, v147, v149
	v_div_fixup_f32 v146, v146, v145, 1.0
	v_lshlrev_b32_e32 v150, 16, v134
	v_lshlrev_b32_e32 v134, 16, v135
	v_and_b32_e32 v135, 0xffff0000, v135
	v_pk_mul_f32 v[150:151], v[146:147], v[150:151] op_sel_hi:[0,1]
	v_pk_mul_f32 v[134:135], v[146:147], v[134:135] op_sel_hi:[0,1]
	v_lshl_add_u64 v[148:149], v[102:103], 0, s[10:11]
	v_pk_fma_f32 v[92:93], v[28:29], v[150:151], v[92:93]
	v_pk_fma_f32 v[94:95], v[30:31], v[134:135], v[94:95]
	global_store_dwordx4 v[148:149], v[92:95], off nt
	s_waitcnt vmcnt(27)
	s_nop 0
	v_lshlrev_b32_e32 v92, 16, v132
	v_and_b32_e32 v93, 0xffff0000, v132
	v_pk_mul_f32 v[92:93], v[146:147], v[92:93] op_sel_hi:[0,1]
	v_pk_fma_f32 v[88:89], v[24:25], v[92:93], v[88:89]
	v_lshlrev_b32_e32 v92, 16, v133
	v_and_b32_e32 v93, 0xffff0000, v133
	v_pk_mul_f32 v[92:93], v[146:147], v[92:93] op_sel_hi:[0,1]
	v_pk_fma_f32 v[90:91], v[26:27], v[92:93], v[90:91]
	global_store_dwordx4 v[148:149], v[88:91], off offset:1024 nt
	s_waitcnt vmcnt(27)
; __device__ __forceinline__ float bf_lo(unsigned u) { return __uint_as_float(u << 16); }
; __device__ __forceinline__ float bf_hi(unsigned u) { return __uint_as_float(u & 0xffff0000u); }
; __global__ void __launch_bounds__(NTHR, 2) mk_fwd(Args a) {
;     ...
;             for (int r = 0; r < 2; ++r) { const int m = m0 + r * NGW;
;                 const float rs = 1.0f / sqrtf(wave_sum(part[r]) * (1.0f / DMODEL) + EPS);
;                 if (m < NTOK) { f32x4* orow = (f32x4*)(a.out + (size_t)m * DMODEL) + lane;
; #pragma unroll
;                     for (int j = 0; j < 8; ++j) { const f32x4 xx = xv[r][j], g4 = gv[j]; const u32x2 o = ov[r][j];
;                         f32x4 res; res[0] = xx[0] + bf_lo(o.x) * rs * g4[0]; res[1] = xx[1] + bf_hi(o.x) * rs * g4[1]; res[2] = xx[2] + bf_lo(o.y) * rs * g4[2]; res[3] = xx[3] + bf_hi(o.y) * rs * g4[3];
;                         __builtin_nontemporal_store(res, orow + 64 * j); } } }
	s_nop 0
	v_lshlrev_b32_e32 v88, 16, v130
	v_and_b32_e32 v89, 0xffff0000, v130
	v_pk_mul_f32 v[88:89], v[146:147], v[88:89] op_sel_hi:[0,1]
	v_pk_fma_f32 v[84:85], v[20:21], v[88:89], v[84:85]
	v_lshlrev_b32_e32 v88, 16, v131
	v_and_b32_e32 v89, 0xffff0000, v131
	v_pk_mul_f32 v[88:89], v[146:147], v[88:89] op_sel_hi:[0,1]
	v_pk_fma_f32 v[86:87], v[22:23], v[88:89], v[86:87]
	global_store_dwordx4 v[148:149], v[84:87], off offset:2048 nt
	s_waitcnt vmcnt(27)
	s_nop 0
	v_lshlrev_b32_e32 v84, 16, v128
	v_and_b32_e32 v85, 0xffff0000, v128
	v_pk_mul_f32 v[84:85], v[146:147], v[84:85] op_sel_hi:[0,1]
	v_pk_fma_f32 v[80:81], v[16:17], v[84:85], v[80:81]
	v_lshlrev_b32_e32 v84, 16, v129
	v_and_b32_e32 v85, 0xffff0000, v129
	v_pk_mul_f32 v[84:85], v[146:147], v[84:85] op_sel_hi:[0,1]
	v_pk_fma_f32 v[82:83], v[18:19], v[84:85], v[82:83]
	global_store_dwordx4 v[148:149], v[80:83], off offset:3072 nt
	s_waitcnt vmcnt(23)
	s_nop 0
	v_lshlrev_b32_e32 v80, 16, v126
	v_and_b32_e32 v81, 0xffff0000, v126
	v_pk_mul_f32 v[80:81], v[146:147], v[80:81] op_sel_hi:[0,1]
	v_pk_fma_f32 v[76:77], v[12:13], v[80:81], v[76:77]
	v_lshlrev_b32_e32 v80, 16, v127
	v_and_b32_e32 v81, 0xffff0000, v127
	v_pk_mul_f32 v[80:81], v[146:147], v[80:81] op_sel_hi:[0,1]
	v_pk_fma_f32 v[78:79], v[14:15], v[80:81], v[78:79]
	v_add_co_u32_e32 v80, vcc, s15, v148
	s_nop 1
	v_addc_co_u32_e32 v81, vcc, 0, v149, vcc
	global_store_dwordx4 v[80:81], v[76:79], off nt
	s_waitcnt vmcnt(21)
	ds_bpermute_b32 v78, v136, v144
	s_andn2_b64 vcc, exec, s[8:9]
	v_lshlrev_b32_e32 v76, 16, v124
	v_and_b32_e32 v77, 0xffff0000, v124
	v_pk_mul_f32 v[76:77], v[146:147], v[76:77] op_sel_hi:[0,1]
	v_pk_fma_f32 v[72:73], v[8:9], v[76:77], v[72:73]
	v_lshlrev_b32_e32 v76, 16, v125
	v_and_b32_e32 v77, 0xffff0000, v125
	v_pk_mul_f32 v[76:77], v[146:147], v[76:77] op_sel_hi:[0,1]
	v_pk_fma_f32 v[74:75], v[10:11], v[76:77], v[74:75]
	global_store_dwordx4 v[80:81], v[72:75], off offset:1024 nt
	s_waitcnt lgkmcnt(0)
	s_nop 0
	v_add_f32_e32 v74, v144, v78
	ds_bpermute_b32 v75, v137, v74
	v_lshlrev_b32_e32 v72, 16, v122
	v_and_b32_e32 v73, 0xffff0000, v122
	v_pk_mul_f32 v[72:73], v[146:147], v[72:73] op_sel_hi:[0,1]
	v_pk_fma_f32 v[68:69], v[4:5], v[72:73], v[68:69]
	s_waitcnt lgkmcnt(0)
	v_add_f32_e32 v74, v74, v75
	ds_bpermute_b32 v75, v138, v74
	v_lshlrev_b32_e32 v72, 16, v123
	v_and_b32_e32 v73, 0xffff0000, v123
	v_pk_mul_f32 v[72:73], v[146:147], v[72:73] op_sel_hi:[0,1]
	v_pk_fma_f32 v[70:71], v[6:7], v[72:73], v[70:71]
	global_store_dwordx4 v[80:81], v[68:71], off offset:2048 nt
	s_waitcnt lgkmcnt(0)
	s_nop 0
	v_add_f32_e32 v70, v74, v75
	ds_bpermute_b32 v71, v139, v70
	v_lshlrev_b32_e32 v68, 16, v118
	v_and_b32_e32 v69, 0xffff0000, v118
	v_pk_mul_f32 v[68:69], v[146:147], v[68:69] op_sel_hi:[0,1]
	v_pk_fma_f32 v[68:69], v[0:1], v[68:69], v[60:61]
	s_waitcnt lgkmcnt(0)
	v_add_f32_e32 v72, v70, v71
	ds_bpermute_b32 v73, v140, v72
	v_lshlrev_b32_e32 v60, 16, v119
	v_and_b32_e32 v61, 0xffff0000, v119
	v_pk_mul_f32 v[60:61], v[146:147], v[60:61] op_sel_hi:[0,1]
	v_pk_fma_f32 v[70:71], v[2:3], v[60:61], v[62:63]
	s_waitcnt lgkmcnt(0)
	v_add_f32_e32 v60, v72, v73
	ds_bpermute_b32 v61, v141, v60
	global_store_dwordx4 v[80:81], v[68:71], off offset:3072 nt
	s_cbranch_vccnz .LBB0_839
; __device__ __forceinline__ float bf_lo(unsigned u) { return __uint_as_float(u << 16); }
; __device__ __forceinline__ float bf_hi(unsigned u) { return __uint_as_float(u & 0xffff0000u); }
; __global__ void __launch_bounds__(NTHR, 2) mk_fwd(Args a) {
;     ...
;             for (int r = 0; r < 2; ++r) { const int m = m0 + r * NGW;
;                 const float rs = 1.0f / sqrtf(wave_sum(part[r]) * (1.0f / DMODEL) + EPS);
;                 if (m < NTOK) { f32x4* orow = (f32x4*)(a.out + (size_t)m * DMODEL) + lane;
; #pragma unroll
;                     for (int j = 0; j < 8; ++j) { const f32x4 xx = xv[r][j], g4 = gv[j]; const u32x2 o = ov[r][j];
;                         f32x4 res; res[0] = xx[0] + bf_lo(o.x) * rs * g4[0]; res[1] = xx[1] + bf_hi(o.x) * rs * g4[1]; res[2] = xx[2] + bf_lo(o.y) * rs * g4[2]; res[3] = xx[3] + bf_hi(o.y) * rs * g4[3];
;                         __builtin_nontemporal_store(res, orow + 64 * j); } } }
	s_waitcnt lgkmcnt(0)
	v_add_f32_e32 v60, v60, v61
	v_fmamk_f32 v60, v60, 0x3a000000, v142
	v_mul_f32_e32 v61, 0x4f800000, v60
	v_cmp_gt_f32_e32 vcc, s17, v60
	s_ashr_i32 s7, s6, 31
	s_nop 0
	v_cndmask_b32_e32 v60, v60, v61, vcc
	v_sqrt_f32_e32 v61, v60
	s_nop 0
	v_add_u32_e32 v62, -1, v61
	v_fma_f32 v68, -v62, v61, v60
	v_add_u32_e32 v63, 1, v61
	v_cmp_ge_f32_e64 s[2:3], 0, v68
	s_nop 1
	v_cndmask_b32_e64 v62, v61, v62, s[2:3]
	v_fma_f32 v61, -v63, v61, v60
	v_cmp_lt_f32_e64 s[2:3], 0, v61
	s_nop 1
	v_cndmask_b32_e64 v61, v62, v63, s[2:3]
	v_mul_f32_e32 v62, 0x37800000, v61
	v_cndmask_b32_e32 v61, v61, v62, vcc
	v_cmp_class_f32_e32 vcc, v60, v143
	s_nop 1
	v_cndmask_b32_e32 v60, v61, v60, vcc
	v_div_scale_f32 v61, s[2:3], v60, v60, 1.0
	v_rcp_f32_e32 v62, v61
	s_lshl_b64 s[2:3], s[6:7], 13
	v_lshl_add_u64 v[70:71], v[102:103], 0, s[2:3]
	v_fma_f32 v63, -v61, v62, 1.0
	v_fmac_f32_e32 v62, v63, v62
	v_div_scale_f32 v63, vcc, 1.0, v60, 1.0
	v_mul_f32_e32 v68, v63, v62
	v_fma_f32 v69, -v61, v68, v63
	v_fmac_f32_e32 v68, v69, v62
	v_fma_f32 v61, -v61, v68, v63
	v_div_fmas_f32 v61, v61, v62, v68
	v_div_fixup_f32 v68, v61, v60, 1.0
	s_waitcnt vmcnt(19)
	v_lshlrev_b32_e32 v60, 16, v120
	v_and_b32_e32 v61, 0xffff0000, v120
	v_lshlrev_b32_e32 v62, 16, v121
	v_and_b32_e32 v63, 0xffff0000, v121
	v_pk_mul_f32 v[60:61], v[68:69], v[60:61] op_sel_hi:[0,1]
	v_pk_mul_f32 v[62:63], v[68:69], v[62:63] op_sel_hi:[0,1]
	v_pk_fma_f32 v[60:61], v[28:29], v[60:61], v[64:65]
	v_pk_fma_f32 v[62:63], v[30:31], v[62:63], v[66:67]
	global_store_dwordx4 v[70:71], v[60:63], off nt
	s_waitcnt vmcnt(19)
	s_nop 0
	v_lshlrev_b32_e32 v60, 16, v116
	v_and_b32_e32 v61, 0xffff0000, v116
	v_pk_mul_f32 v[60:61], v[68:69], v[60:61] op_sel_hi:[0,1]
	v_pk_fma_f32 v[56:57], v[24:25], v[60:61], v[56:57]
	v_lshlrev_b32_e32 v60, 16, v117
	v_and_b32_e32 v61, 0xffff0000, v117
	v_pk_mul_f32 v[60:61], v[68:69], v[60:61] op_sel_hi:[0,1]
	v_pk_fma_f32 v[58:59], v[26:27], v[60:61], v[58:59]
	global_store_dwordx4 v[70:71], v[56:59], off offset:1024 nt
	s_waitcnt vmcnt(19)
	s_nop 0
	v_lshlrev_b32_e32 v56, 16, v114
	v_and_b32_e32 v57, 0xffff0000, v114
	v_pk_mul_f32 v[56:57], v[68:69], v[56:57] op_sel_hi:[0,1]
	v_pk_fma_f32 v[52:53], v[20:21], v[56:57], v[52:53]
	v_lshlrev_b32_e32 v56, 16, v115
	v_and_b32_e32 v57, 0xffff0000, v115
	v_pk_mul_f32 v[56:57], v[68:69], v[56:57] op_sel_hi:[0,1]
	v_pk_fma_f32 v[54:55], v[22:23], v[56:57], v[54:55]
	global_store_dwordx4 v[70:71], v[52:55], off offset:2048 nt
	s_waitcnt vmcnt(19)
	s_nop 0
	v_lshlrev_b32_e32 v52, 16, v110
	v_and_b32_e32 v53, 0xffff0000, v110
	v_pk_mul_f32 v[52:53], v[68:69], v[52:53] op_sel_hi:[0,1]
	v_pk_fma_f32 v[44:45], v[16:17], v[52:53], v[44:45]
	v_lshlrev_b32_e32 v52, 16, v111
	v_and_b32_e32 v53, 0xffff0000, v111
	v_pk_mul_f32 v[52:53], v[68:69], v[52:53] op_sel_hi:[0,1]
	v_pk_fma_f32 v[46:47], v[18:19], v[52:53], v[46:47]
	global_store_dwordx4 v[70:71], v[44:47], off offset:3072 nt
	s_waitcnt vmcnt(15)
	s_nop 0
	v_lshlrev_b32_e32 v44, 16, v112
	v_and_b32_e32 v45, 0xffff0000, v112
	v_pk_mul_f32 v[44:45], v[68:69], v[44:45] op_sel_hi:[0,1]
	v_lshlrev_b32_e32 v46, 16, v113
	v_and_b32_e32 v47, 0xffff0000, v113
	v_pk_fma_f32 v[44:45], v[12:13], v[44:45], v[48:49]
	v_pk_mul_f32 v[46:47], v[68:69], v[46:47] op_sel_hi:[0,1]
	v_add_co_u32_e32 v48, vcc, s15, v70
	v_pk_fma_f32 v[46:47], v[14:15], v[46:47], v[50:51]
	s_nop 0
	v_addc_co_u32_e32 v49, vcc, 0, v71, vcc
	global_store_dwordx4 v[48:49], v[44:47], off nt
	s_waitcnt vmcnt(15)
	s_nop 0
	v_lshlrev_b32_e32 v44, 16, v108
	v_and_b32_e32 v45, 0xffff0000, v108
	v_pk_mul_f32 v[44:45], v[68:69], v[44:45] op_sel_hi:[0,1]
	v_pk_fma_f32 v[40:41], v[8:9], v[44:45], v[40:41]
	v_lshlrev_b32_e32 v44, 16, v109
	v_and_b32_e32 v45, 0xffff0000, v109
	v_pk_mul_f32 v[44:45], v[68:69], v[44:45] op_sel_hi:[0,1]
	v_pk_fma_f32 v[42:43], v[10:11], v[44:45], v[42:43]
	global_store_dwordx4 v[48:49], v[40:43], off offset:1024 nt
	s_waitcnt vmcnt(15)
	s_nop 0
	v_lshlrev_b32_e32 v40, 16, v106
	v_and_b32_e32 v41, 0xffff0000, v106
	v_pk_mul_f32 v[40:41], v[68:69], v[40:41] op_sel_hi:[0,1]
	v_pk_fma_f32 v[36:37], v[4:5], v[40:41], v[36:37]
	v_lshlrev_b32_e32 v40, 16, v107
	v_and_b32_e32 v41, 0xffff0000, v107
	v_pk_mul_f32 v[40:41], v[68:69], v[40:41] op_sel_hi:[0,1]
	v_pk_fma_f32 v[38:39], v[6:7], v[40:41], v[38:39]
	global_store_dwordx4 v[48:49], v[36:39], off offset:2048 nt
	s_waitcnt vmcnt(15)
	s_nop 0
	v_lshlrev_b32_e32 v36, 16, v104
	v_and_b32_e32 v37, 0xffff0000, v104
	v_pk_mul_f32 v[36:37], v[68:69], v[36:37] op_sel_hi:[0,1]
	v_pk_fma_f32 v[32:33], v[0:1], v[36:37], v[32:33]
	v_lshlrev_b32_e32 v36, 16, v105
	v_and_b32_e32 v37, 0xffff0000, v105
	v_pk_mul_f32 v[36:37], v[68:69], v[36:37] op_sel_hi:[0,1]
	v_pk_fma_f32 v[34:35], v[2:3], v[36:37], v[34:35]
	global_store_dwordx4 v[48:49], v[32:35], off offset:3072 nt
	s_branch .LBB0_839
.Lp4_dmyA0:
	global_load_dword v152, v153, s[52:53]
	global_load_dword v152, v153, s[52:53]
	global_load_dword v152, v153, s[52:53]
	global_load_dword v152, v153, s[52:53]
	s_branch .Lp4_retA0

; __global__ void __launch_bounds__(NTHR, 2) mk_fwd(Args a) {
;     ...
;             for (int r = 0; r < 2; ++r) { const int m = m0 + r * NGW; const bool ok = m < NTOK; const int mm = ok ? m : m0;
;                 part[r] = (lane < 32) ? OSS[(size_t)mm * 32 + lane] : 0.f;
;                 const f32x4* xr = (const f32x4*)(x + (size_t)mm * DMODEL) + lane; const u32x2* ob = (const u32x2*)(OutB + (size_t)mm * DMODEL) + lane;
; #pragma unroll
;                 for (int j = 0; j < 8; ++j) { xv[r][j] = __builtin_nontemporal_load(xr + 64 * j); ov[r][j] = __builtin_nontemporal_load(ob + 64 * j); } }
.Lp4_dmyB4:
	global_load_dword v152, v153, s[52:53]
	global_load_dword v152, v153, s[52:53]
	s_branch .Lp4_retB4
